# in-proj layer-0 start delay of the slack CUs: 5 sleeps instead of 4 (on the sc1 nt version)
# baseline (speedup 1.0000x reference)
; __global__ void __launch_bounds__(512, 2) mega(P p) {
;     ...
;   for (int ph = p.pb; ph < p.pe; ++ph) {
;     if (ph == 0) phase_prep(p, lds);
;     else if (ph == 1) phase_h0(p);
;     else {
;       const int l = (ph - 2) >> 2, s = (ph - 2) & 3;
;       if (s == 0) { for (int rr = 0; rr < REP_INPROJ; ++rr) { if (rr) cg::this_grid().sync(); phase_inproj(p, l, lds); } }
;       else if (s == 1) { for (int rr = 0; rr < REP_MIX; ++rr) { if (rr) cg::this_grid().sync(); phase_mix(p, l, rr, lds); } }
.LBB0_74:
	s_andn2_b64 vcc, exec, s[0:1]
	s_cbranch_vccnz .LBB0_941
	s_cmp_lg_u32 s24, 1
	s_mov_b64 s[0:1], -1
	s_cbranch_scc0 .LBB0_812
	v_readlane_b32 s0, v254, 9
	v_readlane_b32 s1, v254, 10
	v_mov_b32_e32 v0, v195
	s_andn2_b64 vcc, exec, s[0:1]
	s_cbranch_vccnz .LBB0_811
	s_cmp_lg_u32 s50, 0
	s_cbranch_scc1 .Ldephase_in_done
	s_cmp_lt_u32 s84, 14
	s_cbranch_scc1 .Ldephase_in_done
	s_sleep 127
	s_sleep 127
	s_sleep 127
	s_sleep 127
	s_sleep 127
